# v15 + QKV phase: CUs with 6 of 7 tiles run the (hand-unrolled, 8-loads-in-flight) band-buffer copy BEFORE their GEMM tiles instead of after: no idle tail and their f32 epilogue store bursts are de-pha
# speedup vs baseline: 1.0169x; 1.0052x over previous
;     __device__ __forceinline__ bool next(int i, Unit& u) const { const int L = i * G + c; if (L >= nunits) return false; const int t = L / S, ks = L % S; u.pm = pm0 + t / nN; u.pn = t % nN; u.ko = ks * Ksub; return true; }
;     __host__ __device__ bool next(int i, Unit& u) const {
;         const long L = (long)i * G + c; if (L >= nwg) return false;
;         int wgid = (int)L; { const int q = nwg / NXCD, r = nwg % NXCD, xcd = wgid % NXCD, off = wgid / NXCD; wgid = (xcd < r ? xcd * (q + 1) : r * (q + 1) + (xcd - r) * q) + off; }
;         const int nig = WGM * nN, gid = wgid / nig, fm = gid * WGM, gsz = (nM - fm) < WGM ? (nM - fm) : WGM;
;         u.pm = fm + ((wgid % nig) % gsz); u.pn = (wgid % nig) / gsz; u.ko = 0; return true;
; __global__ void __launch_bounds__(512, 2) fwd(Args args) {
;     ...
;     if (IN(10)) { pg8::Gemm g{Xb, Wt_inc, M, IN_C, DM, DM}; pg8::StaticOrder S; S.init(M, IN_C, G, bx); typedef pg8::EpiQKV<O_SKP, O_SVP, O_SKS, O_SVS, MP, IN_C> EQ; EQ E{Hb, out};
;         pg8::gemm_phase<EQ, pg8::StaticOrder, true, true>(lds, g, S, E);
;         { const bool part = (G == 256); if (!part || bx >= 96) { const size_t gtx = part ? (size_t)(bx - 96) * 512 + tid : gt, gnx = part ? (size_t)160 * 512 : gn;
.LBB0_1264:
	s_cmp_lt_i32 s78, 11
	s_cselect_b64 s[0:1], -1, 0
	s_and_b64 s[6:7], s[0:1], s[4:5]
	s_andn2_b64 vcc, exec, s[6:7]
	s_cbranch_vccnz .LBB0_1288
	s_mov_b32 s98, 0
	s_cmpk_lg_i32 s96, 0x100
	s_cbranch_scc1 .Lp10_gemm
	s_cmpk_lt_i32 s74, 0x60
	s_cbranch_scc1 .Lp10_gemm
	s_mov_b32 s98, 1
	s_mov_b64 s[0:1], 0
	s_branch .Lp10_copy
.Lp10_gemm:
	s_cmpk_gt_i32 s74, 0x65f
	v_readfirstlane_b32 s5, v198
	s_cbranch_scc1 .LBB0_1283
	v_lshrrev_b32_e32 v1, 5, v198
	v_lshrrev_b32_e32 v3, 1, v198
	v_and_b32_e32 v1, 4, v1
	v_bfe_u32 v2, v198, 2, 2
	s_waitcnt vmcnt(0)
	v_and_b32_e32 v12, 24, v3
	v_add_u32_e32 v10, 0x2000, v233
	v_or3_b32 v1, v1, v2, v12
	v_lshrrev_b32_e32 v2, 7, v10
	s_movk_i32 s0, 0xe0
	v_and_or_b32 v3, v2, s0, v1
	s_movk_i32 s0, 0xf0
	v_bitop3_b32 v11, v233, v235, 48 bitop3:0x6c
	v_and_or_b32 v2, v2, s0, v230
	s_movk_i32 s0, 0x60
	v_or_b32_e32 v4, v11, v205
	v_and_or_b32 v1, v231, s0, v1
	s_movk_i32 s0, 0x70
	v_lshl_or_b32 v134, v1, 11, v4
	v_and_or_b32 v1, v231, s0, v230
	s_lshr_b32 s0, s75, 29
	s_add_i32 s0, s74, s0
	s_lshr_b32 s8, s5, 6
	s_ashr_i32 s1, s0, 3
	s_and_b32 s0, s0, -8
	s_lshr_b32 s10, s5, 8
	s_lshl_b32 s2, s8, 10
	s_sub_i32 s0, s74, s0
	s_cmp_lt_i32 s0, 0
	s_movk_i32 s3, 0xcd
	s_cselect_b32 s4, s3, 0xcc
	s_mul_i32 s0, s0, s4
	s_add_i32 s0, s0, s1
	s_mul_hi_i32 s1, s0, 0x2aaaaaab
	s_lshr_b32 s4, s1, 31
	s_ashr_i32 s1, s1, 4
	s_add_i32 s1, s1, s4
	s_lshl_b32 s9, s1, 3
	s_mulk_i32 s1, 0x60
	s_sub_i32 s0, s0, s1
	s_bfe_i32 s1, s0, 0x80000
	s_bfe_u32 s1, s1, 0x3000c
	s_add_i32 s1, s0, s1
	s_bfe_i32 s4, s1, 0x80000
	s_and_b32 s1, s1, 0xf8
	s_sub_i32 s0, s0, s1
	s_sext_i32_i16 s4, s4
	s_sext_i32_i8 s0, s0
	s_lshr_b32 s4, s4, 3
	s_add_i32 s20, s9, s0
	s_ashr_i32 s21, s20, 31
	s_bfe_i64 s[12:13], s[4:5], 0x100000
	s_lshl_b64 s[0:1], s[20:21], 19
	s_lshl_b64 s[12:13], s[12:13], 19
	s_add_u32 s24, s60, s12
	s_addc_u32 s25, s61, s13
	s_add_i32 s21, s2, 0x100
	s_add_i32 m0, s21, 0x10000
	v_lshl_or_b32 v130, v3, 11, v4
	global_load_lds_dwordx4 v134, s[24:25]
	s_add_i32 m0, s21, 0x12000
	s_add_u32 s12, s24, 0x40000
	global_load_lds_dwordx4 v130, s[24:25]
	s_addc_u32 s13, s25, 0
	s_add_i32 m0, s21, 0x14000
	v_lshl_or_b32 v136, v1, 11, v4
	global_load_lds_dwordx4 v134, s[12:13]
	s_add_i32 m0, s21, 0x16000
	s_add_u32 s22, s68, s0
	s_addc_u32 s23, s69, s1
	s_add_i32 s28, s21, 0x2000
	global_load_lds_dwordx4 v130, s[12:13]
	s_mov_b32 m0, s21
	s_add_u32 s0, s22, 0x40000
	v_lshl_or_b32 v132, v2, 11, v4
	global_load_lds_dwordx4 v136, s[22:23]
	s_mov_b32 m0, s28
	s_addc_u32 s1, s23, 0
	s_add_i32 s29, s21, 0x4000
	global_load_lds_dwordx4 v132, s[22:23]
	s_mov_b32 m0, s29
	s_add_i32 s30, s21, 0x6000
	global_load_lds_dwordx4 v136, s[0:1]
	s_mov_b32 m0, s30
	v_mov_b32_e32 v135, 0
	global_load_lds_dwordx4 v132, s[0:1]
	v_mov_b32_e32 v131, v135
	v_mov_b32_e32 v137, v135
	v_mov_b32_e32 v133, v135
	s_cmp_eq_u32 s10, 1
	s_mov_b32 s31, 0
	s_mov_b32 s33, 0x10000
	v_lshl_add_u64 v[8:9], s[24:25], 0, v[134:135]
	v_lshl_add_u64 v[4:5], s[24:25], 0, v[130:131]
	s_mov_b32 s12, 0x14000
	v_lshl_add_u64 v[2:3], s[22:23], 0, v[136:137]
	s_cselect_b64 s[0:1], -1, 0
	s_cmp_lg_u32 s10, 1
	v_lshl_add_u64 v[6:7], s[22:23], 0, v[132:133]
	s_cbranch_scc1 .LBB0_1268
	s_barrier

; __global__ void __launch_bounds__(512, 2) fwd(Args args) {
;     ...
;         { const bool part = (G == 256); if (!part || bx >= 96) { const size_t gtx = part ? (size_t)(bx - 96) * 512 + tid : gt, gnx = part ? (size_t)160 * 512 : gn;
;         for (size_t i = gtx; i < (size_t)DB * 448 * 128; i += gnx) { const size_t b = i / (448 * 128), rem = i % (448 * 128);
;             __builtin_nontemporal_store(__builtin_nontemporal_load((const f32x4*)(c_bk + b * 512 * 512 + 64 * 512 + rem * 4)), (f32x4*)(out + O_BKS + b * 512 * 512 + rem * 4));
;             __builtin_nontemporal_store(__builtin_nontemporal_load((const f32x4*)(c_bv + b * 512 * 512 + 64 * 512 + rem * 4)), (f32x4*)(out + O_BVS + b * 512 * 512 + rem * 4)); }
;         } } }
.LBB0_1283:
	s_cmp_eq_u32 s98, 1
	s_cbranch_scc1 .LBB0_1288
	s_cmpk_lg_i32 s96, 0x100
	s_cselect_b64 s[0:1], -1, 0
	s_cmpk_eq_i32 s96, 0x100
	s_cselect_b64 s[2:3], -1, 0
	s_cmpk_lt_i32 s74, 0x60
	s_cselect_b64 s[4:5], -1, 0
	s_and_b64 s[2:3], s[4:5], s[2:3]
	s_and_b64 vcc, exec, s[2:3]
	s_cbranch_vccnz .LBB0_1288
.Lp10_copy:
	s_lshl_b32 s2, s74, 9
	s_add_i32 s2, s2, 0xffff4000
	v_add_u32_e32 v2, s2, v198
	s_mov_b32 s14, 0x1bffff
	v_cndmask_b32_e64 v2, v2, v206, s[0:1]
	v_cmp_ge_u32_e32 vcc, s14, v2
	s_and_saveexec_b64 s[4:5], vcc
	s_cbranch_execz .LBB0_1287
	s_and_b64 s[0:1], s[0:1], exec
	v_readlane_b32 s3, v251, 45
	v_readlane_b32 s24, v250, 3
	v_readlane_b32 s25, v250, 4
	v_readlane_b32 s26, v250, 5
	v_readlane_b32 s27, v250, 6
	v_readlane_b32 s22, v251, 25
	v_readlane_b32 s23, v251, 26
	s_nop 3
	s_cselect_b32 s0, s3, 0x14000
	s_add_u32 s24, s24, 0x20000
	s_addc_u32 s25, s25, 0
	s_add_u32 s26, s26, 0x20000
	s_addc_u32 s27, s27, 0
	s_add_u32 s8, s22, 0x1be40000
	s_addc_u32 s9, s23, 0
	s_add_u32 s10, s22, 0x1de40000
	s_addc_u32 s11, s23, 0
	s_lshl_b32 s1, s0, 2
	s_mov_b32 s2, 0x24924925
	s_mov_b64 s[12:13], 0
.Lbcopy_loop:
	v_add_u32_e32 v3, s0, v2
	v_lshl_add_u32 v4, s0, 1, v2
	v_min_u32_e32 v3, s14, v3
	v_add_u32_e32 v5, s0, v4
	v_min_u32_e32 v4, s14, v4
	v_min_u32_e32 v5, s14, v5
	v_lshrrev_b32_e32 v6, 13, v2
	v_lshrrev_b32_e32 v7, 13, v3
	v_lshrrev_b32_e32 v8, 13, v4
	v_lshrrev_b32_e32 v9, 13, v5
	v_mul_hi_u32 v6, v6, s2
	v_mul_hi_u32 v7, v7, s2
	v_mul_hi_u32 v8, v8, s2
	v_mul_hi_u32 v9, v9, s2
	v_mul_u32_u24_e32 v10, 0xe000, v6
	v_mul_u32_u24_e32 v11, 0xe000, v7
	v_mul_u32_u24_e32 v12, 0xe000, v8
	v_mul_u32_u24_e32 v13, 0xe000, v9
	v_sub_u32_e32 v10, v2, v10
	v_sub_u32_e32 v11, v3, v11
	v_sub_u32_e32 v12, v4, v12
	v_sub_u32_e32 v13, v5, v13
	v_lshlrev_b32_e32 v10, 4, v10
	v_lshlrev_b32_e32 v11, 4, v11
	v_lshlrev_b32_e32 v12, 4, v12
	v_lshlrev_b32_e32 v13, 4, v13
	v_lshl_add_u32 v6, v6, 20, v10
	v_lshl_add_u32 v7, v7, 20, v11
	v_lshl_add_u32 v8, v8, 20, v12
	v_lshl_add_u32 v9, v9, 20, v13
	global_load_dwordx4 v[16:19], v6, s[24:25] nt
	global_load_dwordx4 v[20:23], v6, s[26:27] nt
	global_load_dwordx4 v[24:27], v7, s[24:25] nt
	global_load_dwordx4 v[28:31], v7, s[26:27] nt
	global_load_dwordx4 v[32:35], v8, s[24:25] nt
	global_load_dwordx4 v[36:39], v8, s[26:27] nt
	global_load_dwordx4 v[40:43], v9, s[24:25] nt
	global_load_dwordx4 v[44:47], v9, s[26:27] nt
	v_add_u32_e32 v2, s1, v2
	v_cmp_lt_u32_e32 vcc, s14, v2
	s_or_b64 s[12:13], vcc, s[12:13]
	s_waitcnt vmcnt(7)
	global_store_dwordx4 v6, v[16:19], s[8:9] nt
	s_waitcnt vmcnt(7)
	global_store_dwordx4 v6, v[20:23], s[10:11] nt
	s_waitcnt vmcnt(7)
	global_store_dwordx4 v7, v[24:27], s[8:9] nt
	s_waitcnt vmcnt(7)
	global_store_dwordx4 v7, v[28:31], s[10:11] nt
	s_waitcnt vmcnt(7)
	global_store_dwordx4 v8, v[32:35], s[8:9] nt
	s_waitcnt vmcnt(7)
	global_store_dwordx4 v8, v[36:39], s[10:11] nt
	s_waitcnt vmcnt(7)
	global_store_dwordx4 v9, v[40:43], s[8:9] nt
	s_waitcnt vmcnt(7)
	global_store_dwordx4 v9, v[44:47], s[10:11] nt
	s_andn2_b64 exec, exec, s[12:13]
	s_cbranch_execnz .Lbcopy_loop
.LBB0_1287:
	s_or_b64 exec, exec, s[4:5]
	s_cmp_eq_u32 s98, 1
	s_cbranch_scc0 .LBB0_1288
	s_waitcnt vmcnt(0)
	s_branch .Lp10_gemm

; __global__ void __launch_bounds__(512, 2) fwd(Args args) {
	.amdhsa_kernel _Z3fwd4Args
		.amdhsa_group_segment_fixed_size 256
		.amdhsa_private_segment_fixed_size 0
		.amdhsa_kernarg_size 464
		.amdhsa_user_sgpr_count 2
		.amdhsa_user_sgpr_dispatch_ptr 0
		.amdhsa_user_sgpr_queue_ptr 0
		.amdhsa_user_sgpr_kernarg_segment_ptr 1
		.amdhsa_user_sgpr_dispatch_id 0
		.amdhsa_user_sgpr_kernarg_preload_length 0
		.amdhsa_user_sgpr_kernarg_preload_offset 0
		.amdhsa_user_sgpr_private_segment_size 0
		.amdhsa_uses_dynamic_stack 0
		.amdhsa_enable_private_segment 0
		.amdhsa_system_sgpr_workgroup_id_x 1
		.amdhsa_system_sgpr_workgroup_id_y 0
		.amdhsa_system_sgpr_workgroup_id_z 0
		.amdhsa_system_sgpr_workgroup_info 0
		.amdhsa_system_vgpr_workitem_id 2
		.amdhsa_next_free_vgpr 252
		.amdhsa_next_free_sgpr 99
		.amdhsa_accum_offset 252
		.amdhsa_reserve_vcc 1
		.amdhsa_float_round_mode_32 0
		.amdhsa_float_round_mode_16_64 0
		.amdhsa_float_denorm_mode_32 3
		.amdhsa_float_denorm_mode_16_64 3
		.amdhsa_dx10_clamp 1
		.amdhsa_ieee_mode 1
		.amdhsa_fp16_overflow 0
		.amdhsa_tg_split 0
		.amdhsa_exception_fp_ieee_invalid_op 0
		.amdhsa_exception_fp_denorm_src 0
		.amdhsa_exception_fp_ieee_div_zero 0
		.amdhsa_exception_fp_ieee_overflow 0
		.amdhsa_exception_fp_ieee_underflow 0
		.amdhsa_exception_fp_ieee_inexact 0
		.amdhsa_exception_int_div_zero 0
	.end_amdhsa_kernel

; __global__ void __launch_bounds__(512, 2) fwd(Args args) {
amdhsa.kernels:
  - .agpr_count:     0
    .args:
      - .offset:         0
        .size:           208
        .value_kind:     by_value
      - .offset:         208
        .size:           4
        .value_kind:     hidden_block_count_x
      - .offset:         212
        .size:           4
        .value_kind:     hidden_block_count_y
      - .offset:         216
        .size:           4
        .value_kind:     hidden_block_count_z
      - .offset:         220
        .size:           2
        .value_kind:     hidden_group_size_x
      - .offset:         222
        .size:           2
        .value_kind:     hidden_group_size_y
      - .offset:         224
        .size:           2
        .value_kind:     hidden_group_size_z
      - .offset:         226
        .size:           2
        .value_kind:     hidden_remainder_x
      - .offset:         228
        .size:           2
        .value_kind:     hidden_remainder_y
      - .offset:         230
        .size:           2
        .value_kind:     hidden_remainder_z
      - .offset:         248
        .size:           8
        .value_kind:     hidden_global_offset_x
      - .offset:         256
        .size:           8
        .value_kind:     hidden_global_offset_y
      - .offset:         264
        .size:           8
        .value_kind:     hidden_global_offset_z
      - .offset:         272
        .size:           2
        .value_kind:     hidden_grid_dims
      - .offset:         296
        .size:           8
        .value_kind:     hidden_multigrid_sync_arg
      - .offset:         328
        .size:           4
        .value_kind:     hidden_dynamic_lds_size
    .group_segment_fixed_size: 256
    .kernarg_segment_align: 8
    .kernarg_segment_size: 464
    .language:       OpenCL C
    .language_version:
      - 2
      - 0
    .max_flat_workgroup_size: 512
    .name:           _Z3fwd4Args
    .private_segment_fixed_size: 0
    .sgpr_count:     105
    .sgpr_spill_count: 127
    .symbol:         _Z3fwd4Args.kd
    .uniform_work_group_size: 1
    .uses_dynamic_stack: false
    .vgpr_count:     252
    .vgpr_spill_count: 0
    .wavefront_size: 64
